# plus: norm2 per-wave column-factor loads (gain, scale, shift) issued together instead of 8 waited groups
# speedup vs baseline: 1.0037x; 1.0037x over previous
.LBB0_1315:
	s_andn2_b64 vcc, exec, s[0:1]
	s_cbranch_vccnz .LBB0_1392
	v_readlane_b32 s0, v253, 49
	v_readlane_b32 s40, v252, 7
	v_readlane_b32 s1, v253, 50
	s_lshl_b32 s4, s0, 11
	v_readlane_b32 s44, v252, 11
	v_readlane_b32 s45, v252, 12
	s_lshl_b64 s[0:1], s[4:5], 2
	v_readlane_b32 s46, v252, 13
	v_readlane_b32 s47, v252, 14
	v_readlane_b32 s48, v252, 15
	v_readlane_b32 s49, v252, 16
	v_readlane_b32 s50, v252, 17
	v_readlane_b32 s51, v252, 18
	v_readlane_b32 s52, v252, 19
	v_readlane_b32 s53, v252, 20
	v_readlane_b32 s54, v252, 21
	v_readlane_b32 s55, v252, 22
	s_mov_b64 s[8:9], s[44:45]
	v_mov_b32_e32 v2, v0
	s_add_u32 s6, s8, s0
	s_addc_u32 s7, s9, s1
	v_readfirstlane_b32 s0, v2
	s_ashr_i32 s0, s0, 6
	v_readlane_b32 s1, v252, 50
	s_add_i32 s8, s1, s0
	s_cmp_ge_i32 s8, s78
	v_readlane_b32 s41, v252, 8
	v_readlane_b32 s42, v252, 9
	v_readlane_b32 s43, v252, 10
	s_mov_b64 s[10:11], s[46:47]
	s_mov_b64 s[12:13], s[48:49]
	s_mov_b64 s[14:15], s[50:51]
	s_mov_b64 s[16:17], s[52:53]
	s_mov_b64 s[18:19], s[54:55]
	s_cbranch_scc1 .LBB0_1325
	v_readlane_b32 s0, v253, 49
	s_mul_i32 s0, s0, 0xc000
	v_readlane_b32 s10, v252, 31
	v_and_b32_e32 v68, 63, v2
	v_readlane_b32 s1, v253, 50
	v_readlane_b32 s11, v252, 32
	s_add_u32 s0, s10, s0
	v_lshlrev_b32_e32 v34, 4, v68
	s_addc_u32 s1, s11, 0
	v_lshl_add_u64 v[10:11], s[0:1], 0, v[34:35]
	s_mov_b64 s[0:1], 0x6000
	v_lshl_add_u64 v[24:25], v[10:11], 0, s[0:1]
	s_mov_b64 s[0:1], 0x8000
	v_lshl_add_u64 v[18:19], v[10:11], 0, s[0:1]
	s_mov_b32 s0, 0x9000
	v_add_co_u32_e32 v32, vcc, s0, v10
	s_nop 1
	v_addc_co_u32_e32 v33, vcc, 0, v11, vcc
	s_movk_i32 s0, 0x7000
	v_add_co_u32_e32 v30, vcc, s0, v10
	s_nop 1
	v_lshl_add_u64 v[22:23], s[6:7], 0, v[34:35]
	v_addc_co_u32_e32 v31, vcc, 0, v11, vcc
	v_add_co_u32_e32 v64, vcc, s91, v22
	s_nop 1
	v_readlane_b32 s0, v255, 59
	v_addc_co_u32_e32 v65, vcc, 0, v23, vcc
	v_readlane_b32 s1, v255, 60
	global_load_dwordx4 v[36:39], v34, s[6:7]
	global_load_dwordx4 v[40:43], v34, s[6:7] offset:1024
	global_load_dwordx4 v[44:47], v34, s[6:7] offset:2048
	global_load_dwordx4 v[48:51], v34, s[6:7] offset:3072
	global_load_dwordx4 v[52:55], v[64:65], off
	global_load_dwordx4 v[56:59], v[64:65], off offset:1024
	global_load_dwordx4 v[60:63], v[64:65], off offset:2048
	global_load_dwordx4 v[166:169], v[32:33], off offset:-4096
	global_load_dwordx4 v[170:173], v[18:19], off offset:1024
	global_load_dwordx4 v[174:177], v[18:19], off offset:2048
	global_load_dwordx4 v[178:181], v[18:19], off offset:3072
	global_load_dwordx4 v[182:185], v[32:33], off
	global_load_dwordx4 v[186:189], v[32:33], off offset:1024
	global_load_dwordx4 v[190:193], v[32:33], off offset:2048
	global_load_dwordx4 v[194:197], v[32:33], off offset:3072
	global_load_dwordx4 v[2:5], v[30:31], off offset:-4096
	global_load_dwordx4 v[6:9], v[24:25], off offset:1024
	global_load_dwordx4 v[10:13], v[24:25], off offset:2048
	global_load_dwordx4 v[14:17], v[24:25], off offset:3072
	global_load_dwordx4 v[18:21], v[30:31], off
	global_load_dwordx4 v[22:25], v[30:31], off offset:1024
	global_load_dwordx4 v[26:29], v[30:31], off offset:2048
	global_load_dwordx4 v[30:33], v[30:31], off offset:3072
	global_load_dwordx4 v[64:67], v[64:65], off offset:3072
	s_waitcnt vmcnt(0)
	v_pk_add_f32 v[168:169], v[168:169], 1.0 op_sel_hi:[1,0]
	v_pk_add_f32 v[166:167], v[166:167], 1.0 op_sel_hi:[1,0]
	v_pk_mul_f32 v[166:167], v[36:37], v[166:167]
	v_pk_mul_f32 v[36:37], v[38:39], v[168:169]
	v_mov_b32_e32 v38, v166
	v_mov_b32_e32 v39, v167
	v_pk_add_f32 v[172:173], v[172:173], 1.0 op_sel_hi:[1,0]
	v_pk_add_f32 v[170:171], v[170:171], 1.0 op_sel_hi:[1,0]
	v_pk_mul_f32 v[170:171], v[40:41], v[170:171]
	v_pk_mul_f32 v[40:41], v[42:43], v[172:173]
	v_mov_b32_e32 v42, v170
	v_mov_b32_e32 v43, v171
	v_pk_add_f32 v[176:177], v[176:177], 1.0 op_sel_hi:[1,0]
	v_pk_add_f32 v[174:175], v[174:175], 1.0 op_sel_hi:[1,0]
	v_pk_mul_f32 v[174:175], v[44:45], v[174:175]
	v_pk_mul_f32 v[44:45], v[46:47], v[176:177]
	v_mov_b32_e32 v46, v174
	v_mov_b32_e32 v47, v175
	v_pk_add_f32 v[180:181], v[180:181], 1.0 op_sel_hi:[1,0]
	v_pk_add_f32 v[178:179], v[178:179], 1.0 op_sel_hi:[1,0]
	v_pk_mul_f32 v[178:179], v[48:49], v[178:179]
	v_pk_mul_f32 v[48:49], v[50:51], v[180:181]
	v_mov_b32_e32 v50, v178
	v_mov_b32_e32 v51, v179
	v_pk_add_f32 v[184:185], v[184:185], 1.0 op_sel_hi:[1,0]
	v_pk_add_f32 v[182:183], v[182:183], 1.0 op_sel_hi:[1,0]
	v_pk_mul_f32 v[182:183], v[52:53], v[182:183]
	v_pk_mul_f32 v[52:53], v[54:55], v[184:185]
	v_mov_b32_e32 v54, v182
	v_mov_b32_e32 v55, v183
	v_pk_add_f32 v[188:189], v[188:189], 1.0 op_sel_hi:[1,0]
	v_pk_add_f32 v[186:187], v[186:187], 1.0 op_sel_hi:[1,0]
	v_pk_mul_f32 v[186:187], v[56:57], v[186:187]
	v_pk_mul_f32 v[56:57], v[58:59], v[188:189]
	v_mov_b32_e32 v58, v186
	v_mov_b32_e32 v59, v187
	v_pk_add_f32 v[192:193], v[192:193], 1.0 op_sel_hi:[1,0]
	v_pk_add_f32 v[190:191], v[190:191], 1.0 op_sel_hi:[1,0]
	v_pk_mul_f32 v[190:191], v[60:61], v[190:191]
	v_pk_mul_f32 v[60:61], v[62:63], v[192:193]
	v_mov_b32_e32 v62, v190
	v_mov_b32_e32 v63, v191
	v_pk_add_f32 v[196:197], v[196:197], 1.0 op_sel_hi:[1,0]
	v_pk_add_f32 v[194:195], v[194:195], 1.0 op_sel_hi:[1,0]
	v_pk_mul_f32 v[194:195], v[64:65], v[194:195]
	v_pk_mul_f32 v[64:65], v[66:67], v[196:197]
	v_mov_b32_e32 v66, v194
	v_mov_b32_e32 v67, v195
	v_xor_b32_e32 v34, 1, v1
	v_cmp_lt_i32_e32 vcc, v34, v242
	s_nop 1
	v_cndmask_b32_e32 v34, v1, v34, vcc
	v_lshlrev_b32_e32 v152, 2, v34
	v_xor_b32_e32 v34, 2, v1
	v_cmp_lt_i32_e32 vcc, v34, v242
	s_nop 1
	v_cndmask_b32_e32 v34, v1, v34, vcc
	v_lshlrev_b32_e32 v153, 2, v34
	v_xor_b32_e32 v34, 4, v1
	v_cmp_lt_i32_e32 vcc, v34, v242
	s_nop 1
	v_cndmask_b32_e32 v34, v1, v34, vcc
	v_lshlrev_b32_e32 v154, 2, v34
	v_xor_b32_e32 v34, 8, v1
	v_cmp_lt_i32_e32 vcc, v34, v242
	s_nop 1
	v_cndmask_b32_e32 v34, v1, v34, vcc
	v_cmp_lt_i32_e32 vcc, v244, v242
	s_nop 1
	v_lshlrev_b32_e32 v155, 2, v34
	v_cndmask_b32_e32 v34, v1, v244, vcc
	v_cmp_lt_i32_e32 vcc, v243, v242
	s_nop 1
	v_lshlrev_b32_e32 v156, 2, v34
	v_cndmask_b32_e32 v34, v1, v243, vcc
	v_lshlrev_b32_e32 v157, 2, v34
	v_lshlrev_b32_e32 v34, 3, v68
	v_lshl_add_u64 v[68:69], s[0:1], 0, v[34:35]
	v_lshl_add_u64 v[70:71], s[84:85], 0, v[34:35]
	s_branch .LBB0_1319
